# hand-written MLA loop v2: one barrier per tile, QK(t+1) MFMAs interleaved with exp/pack of tile t, PV with row sums, double-buffered score registers
# speedup vs baseline: 1.0118x; 1.0118x over previous
; #define LAS __attribute__((address_space(3)))
; #define ATT_BAR() asm volatile("s_waitcnt lgkmcnt(0)\n\ts_barrier" ::: "memory")
; template <int DQK> __device__ __forceinline__ void x1_tile(LAS unsigned char* lds, const bf16x8 (&qf)[2][DQK / 32], const float (&m)[2], f32x4 (&s)[2][4], int fr, int fq) {
;     constexpr int NKS = DQK / 32;
; #pragma unroll
;     for (int q = 0; q < 2; ++q) { const float c = (m[q] > -1e29f) ? -m[q] : 0.f;
; #pragma unroll
;         for (int ss = 0; ss < 4; ++ss) s[q][ss] = (f32x4){c, c, c, c}; }
; #pragma unroll
;     for (int ss = 0; ss < 4; ++ss)
; #pragma unroll
;         for (int ks = 0; ks < NKS; ++ks) {
;             const bf16x8 kf = *(const LAS bf16x8*)(lds + k_off<DQK>(16 * ss + fr, 4 * ks + fq));
; #pragma unroll
;             for (int q = 0; q < 2; ++q) s[q][ss] = __builtin_amdgcn_mfma_f32_16x16x32_bf16(kf, qf[q][ks], s[q][ss], 0, 0, 0);
;         }
; }
; template <int DQK> __device__ __forceinline__ void causal_pass_pipe(LAS unsigned char* lds, const bf16* K0, int p0, const bf16* K1, int p1, const bf16* V, int pv, int thi,
;         const bf16x8 (&qf)[2][DQK / 32], const int (&tpos)[2], int wave_tmin, int wave_tmax, f32x4 (&o)[2][4], int tid) {
;     asm volatile("" : "+v"(tid)); asm volatile("" : "+s"(K0), "+s"(V)); if (DQK == 96) asm volatile("" : "+s"(K1));
;     const int fr = tid & 15, fq = (tid & 63) >> 4;
;     constexpr int SLOT = KL<DQK>::SLOT;
;     float m[2] = {NEG, NEG}, l[2] = {0.f, 0.f};
; #pragma unroll
;     for (int i = 0; i < 2; ++i)
; #pragma unroll
;         for (int dt = 0; dt < 4; ++dt) o[i][dt] = (f32x4){0.f, 0.f, 0.f, 0.f};
;     Stage<DQK> st;
;     {
;         Stage<DQK> st1;
;         stage_load<DQK>(st, K0, p0, K1, p1, V, pv, 0, true, tid);
;         if (thi >= 1) stage_load<DQK>(st1, K0, p0, K1, p1, V, pv, 1, true, tid);
;         stage_store<DQK>(st, lds, true, tid);
;         if (thi >= 1) stage_store<DQK>(st1, lds + SLOT, true, tid);
;     }
;     ATT_BAR();
;     f32x4 sa[2][4], sb[2][4]; bool ca = true, cb = false;
;     x1_tile<DQK>(lds, qf, m, sa, fr, fq);
;     if (63 <= wave_tmin) x2_tile<true>(0, tpos, m, l, o, sa, fq); else x2_tile<false>(0, tpos, m, l, o, sa, fq);
.LBB0_873:
	s_or_b64 exec, exec, s[14:15]
	v_lshl_add_u64 v[44:45], s[8:9], 0, v[44:45]
	v_lshl_add_u64 v[44:45], v[44:45], 0, v[146:147]
	global_load_dwordx4 v[44:47], v[44:45], off
	v_lshrrev_b32_e32 v51, 3, v50
	v_and_b32_e32 v49, 7, v50
	v_bitop3_b32 v51, v51, v49, 15 bitop3:0x6c
	v_lshlrev_b32_e32 v155, 4, v51
	v_lshlrev_b32_e32 v153, 8, v48
	v_add_u32_e32 v51, 0, v155
	v_add_u32_e32 v51, v51, v153
	v_and_b32_e32 v78, 3, v50
	v_lshlrev_b32_e32 v157, 8, v76
	v_and_b32_e32 v79, 15, v76
	s_waitcnt vmcnt(0) lgkmcnt(0)
	ds_write_b128 v51, v[24:27]
	s_and_saveexec_b64 s[8:9], s[6:7]
	v_bitop3_b32 v52, v78, v79, 8 bitop3:0x36
	v_lshlrev_b32_e32 v52, 4, v52
	v_add3_u32 v52, 0, v52, v157
	ds_write_b128 v52, v[28:31]
	s_or_b64 exec, exec, s[8:9]
	v_lshlrev_b32_e32 v146, 4, v49
	v_mul_lo_u32 v159, v48, s76
	v_add_u32_e32 v48, 0, v146
	v_add_u32_e32 v48, v48, v159
	ds_write_b128 v48, v[32:35] offset:16384
	ds_write_b128 v51, v[36:39] offset:26624
	s_and_saveexec_b64 s[8:9], s[6:7]
	v_bitop3_b32 v36, v78, v79, 8 bitop3:0x36
	v_lshlrev_b32_e32 v36, 4, v36
	v_add3_u32 v36, 0, v36, v157
	ds_write_b128 v36, v[40:43] offset:26624
	s_or_b64 exec, exec, s[8:9]
	v_lshrrev_b32_e32 v36, 4, v50
	v_and_b32_e32 v80, 15, v50
	v_lshlrev_b32_e32 v195, 8, v80
	v_bitop3_b32 v36, v36, v80, 3 bitop3:0x6c
	ds_write_b128 v48, v[44:47] offset:43008
	v_add_u32_e32 v56, 0, v195
	v_lshlrev_b32_e32 v196, 4, v36
	s_waitcnt lgkmcnt(0)
	s_barrier
	s_xor_b64 s[58:59], s[10:11], -1
	v_lshrrev_b32_e32 v72, 6, v144
	s_lshl_b32 s8, s20, 2
	v_readfirstlane_b32 s14, v72
	s_mov_b32 s9, s8
	s_or_b32 s8, s8, 3
	s_lshr_b32 s15, s14, 1
	s_add_i32 s9, s9, s15
	s_mov_b32 s21, 2
	s_cmp_lt_u32 s14, 4
	s_cselect_b32 s63, 1, 0
	s_mov_b32 s32, 2
	s_mov_b32 s49, -1
	s_mov_b32 s60, 0
	s_mov_b32 s61, 0
	s_mov_b32 s62, 0xd000
	v_add_u32_e32 v155, v153, v155
	v_add_u32_e32 v159, v146, v159
	v_add_u32_e32 v159, 0x4000, v159
	v_and_b32_e32 v72, 15, v144
	v_bfe_u32 v73, v144, 4, 2
	v_lshlrev_b32_e32 v74, 8, v72
	v_xor_b32_e32 v75, v73, v72
	v_lshl_add_u32 v199, v75, 4, v74
	v_or_b32_e32 v75, 4, v73
	v_xor_b32_e32 v75, v75, v72
	v_lshl_add_u32 v201, v75, 4, v74
	v_or_b32_e32 v75, 8, v73
	v_xor_b32_e32 v75, v75, v72
	v_lshl_add_u32 v210, v75, 4, v74
	v_lshrrev_b32_e32 v75, 2, v72
	v_lshl_add_u32 v75, v73, 2, v75
	v_mul_u32_u24_e32 v75, 0xa0, v75
	v_and_b32_e32 v74, 3, v72
	v_lshl_add_u32 v251, v74, 3, v75
	v_lshlrev_b32_e32 v75, 2, v73
	v_sub_u32_e32 v151, v158, v75
	v_sub_u32_e32 v153, v156, v75
	v_lshrrev_b32_e32 v72, 2, v144
	v_and_b32_e32 v73, 3, v144
	v_or_b32_e32 v74, 8, v73
	v_and_b32_e32 v75, 15, v72
	v_xor_b32_e32 v74, v74, v75
	v_lshlrev_b32_e32 v75, 8, v72
	v_lshl_add_u32 v157, v74, 4, v75
	s_add_u32 s96, s56, s52
	s_addc_u32 s97, s57, s53
	s_add_u32 s96, s96, 0x3802000
	s_addc_u32 s97, s97, 0
	v_lshlrev_b32_e32 v72, 6, v72
	v_lshl_add_u32 v72, v73, 4, v72
	v_mov_b32_e32 v73, 0
	v_lshl_add_u64 v[166:167], s[96:97], 0, v[72:73]
	v_mov_b32_e32 v72, v146
	v_add_u32_e32 v72, 0x40000, v72
	v_lshl_add_u64 v[160:161], v[160:161], 0, v[72:73]
	v_lshl_add_u64 v[162:163], v[162:163], 0, v[72:73]
	global_load_dwordx4 v[60:63], v[160:161], off
	global_load_dwordx4 v[68:71], v[162:163], off
	s_cmp_eq_u32 s63, 0
	s_cbranch_scc1 .Lmla_nok1_0
	global_load_dwordx4 v[64:67], v[166:167], off
.Lmla_nok1_0:
	v_mov_b32_e32 v96, 0
	v_mov_b32_e32 v97, 0
	v_mov_b32_e32 v98, 0
	v_mov_b32_e32 v99, 0
	v_mov_b32_e32 v88, 0
	v_mov_b32_e32 v89, 0
	v_mov_b32_e32 v90, 0
	v_mov_b32_e32 v91, 0
	v_mov_b32_e32 v92, 0
	v_mov_b32_e32 v93, 0
	v_mov_b32_e32 v94, 0
	v_mov_b32_e32 v95, 0
	v_mov_b32_e32 v48, 0
	v_mov_b32_e32 v49, 0
	v_mov_b32_e32 v50, 0
	v_mov_b32_e32 v51, 0
	v_mov_b32_e32 v165, 0
	v_mov_b32_e32 v200, v183
	v_mov_b32_e32 v84, 0
	v_mov_b32_e32 v85, 0
	v_mov_b32_e32 v86, 0
	v_mov_b32_e32 v87, 0
	v_mov_b32_e32 v76, 0
	v_mov_b32_e32 v77, 0
	v_mov_b32_e32 v78, 0
	v_mov_b32_e32 v79, 0
	v_mov_b32_e32 v80, 0
	v_mov_b32_e32 v81, 0
	v_mov_b32_e32 v82, 0
	v_mov_b32_e32 v83, 0
	v_mov_b32_e32 v56, 0
	v_mov_b32_e32 v57, 0
	v_mov_b32_e32 v58, 0
	v_mov_b32_e32 v59, 0
	v_mov_b32_e32 v164, 0
	v_mov_b32_e32 v211, v183
	v_cmp_lt_f32_e64 s[66:67], s77, v200
	v_cmp_lt_f32_e64 s[68:69], s77, v211
	s_nop 1
	v_cndmask_b32_e64 v197, 0, v200, s[66:67]
	v_cndmask_b32_e64 v198, 0, v211, s[68:69]
	v_sub_f32_e32 v204, 0, v197
	v_mov_b32_e32 v205, v204
	v_mov_b32_e32 v206, v204
	v_mov_b32_e32 v207, v204
	v_sub_f32_e32 v252, 0, v198
	v_mov_b32_e32 v253, v252
	v_mov_b32_e32 v254, v252
	v_mov_b32_e32 v255, v252
	v_add_u32_e32 v195, s61, v199
	v_add_u32_e32 v196, s61, v201
	v_add_u32_e32 v73, s61, v210
	ds_read_b128 v[236:239], v195
	ds_read_b128 v[240:243], v196
	ds_read_b128 v[244:247], v73
	s_waitcnt lgkmcnt(0)
	v_mfma_f32_16x16x32_bf16 v[100:103], v[236:239], v[0:3], v[204:207]
	v_mfma_f32_16x16x32_bf16 v[116:119], v[236:239], v[12:15], v[252:255]
	v_mfma_f32_16x16x32_bf16 v[100:103], v[240:243], v[4:7], v[100:103]
	v_mfma_f32_16x16x32_bf16 v[116:119], v[240:243], v[16:19], v[116:119]
	v_mfma_f32_16x16x32_bf16 v[100:103], v[244:247], v[8:11], v[100:103]
	v_mfma_f32_16x16x32_bf16 v[116:119], v[244:247], v[20:23], v[116:119]
	ds_read_b128 v[236:239], v195 offset:4096
	ds_read_b128 v[240:243], v196 offset:4096
	ds_read_b128 v[244:247], v73 offset:4096
	s_waitcnt lgkmcnt(0)
	v_mfma_f32_16x16x32_bf16 v[104:107], v[236:239], v[0:3], v[204:207]
	v_mfma_f32_16x16x32_bf16 v[120:123], v[236:239], v[12:15], v[252:255]
	v_mfma_f32_16x16x32_bf16 v[104:107], v[240:243], v[4:7], v[104:107]
	v_mfma_f32_16x16x32_bf16 v[120:123], v[240:243], v[16:19], v[120:123]
	v_mfma_f32_16x16x32_bf16 v[104:107], v[244:247], v[8:11], v[104:107]
	v_mfma_f32_16x16x32_bf16 v[120:123], v[244:247], v[20:23], v[120:123]
	ds_read_b128 v[236:239], v195 offset:8192
	ds_read_b128 v[240:243], v196 offset:8192
	ds_read_b128 v[244:247], v73 offset:8192
	s_waitcnt lgkmcnt(0)
	v_mfma_f32_16x16x32_bf16 v[108:111], v[236:239], v[0:3], v[204:207]
	v_mfma_f32_16x16x32_bf16 v[124:127], v[236:239], v[12:15], v[252:255]
	v_mfma_f32_16x16x32_bf16 v[108:111], v[240:243], v[4:7], v[108:111]
	v_mfma_f32_16x16x32_bf16 v[124:127], v[240:243], v[16:19], v[124:127]
	v_mfma_f32_16x16x32_bf16 v[108:111], v[244:247], v[8:11], v[108:111]
	v_mfma_f32_16x16x32_bf16 v[124:127], v[244:247], v[20:23], v[124:127]
	ds_read_b128 v[236:239], v195 offset:12288
	ds_read_b128 v[240:243], v196 offset:12288
	ds_read_b128 v[244:247], v73 offset:12288
	s_waitcnt lgkmcnt(0)
	v_mfma_f32_16x16x32_bf16 v[112:115], v[236:239], v[0:3], v[204:207]
	v_mfma_f32_16x16x32_bf16 v[128:131], v[236:239], v[12:15], v[252:255]
	v_mfma_f32_16x16x32_bf16 v[112:115], v[240:243], v[4:7], v[112:115]
	v_mfma_f32_16x16x32_bf16 v[128:131], v[240:243], v[16:19], v[128:131]
	v_mfma_f32_16x16x32_bf16 v[112:115], v[244:247], v[8:11], v[112:115]
	v_mfma_f32_16x16x32_bf16 v[128:131], v[244:247], v[20:23], v[128:131]
	s_nop 7
	s_nop 7
	s_add_i32 s65, s49, 1
	s_cmp_eq_u32 s65, s9
	s_cbranch_scc1 .Lmla_mask1
	s_branch .Lmla_chk1
; #define LAS __attribute__((address_space(3)))
; __device__ __forceinline__ unsigned cvtpk(float lo, float hi) { f32x2_t v = {lo, hi}; bf16x2_t b = __builtin_convertvector(v, bf16x2_t); return __builtin_bit_cast(unsigned, b); }
; template <int I0, int NQ, int VO> __device__ __forceinline__ void tile_y(LAS unsigned char* lds, float (&l)[2], f32x4 (&o)[2][4], f32x4 (&s)[2][4], int fr, int fq) {
;     bf16x8 pb[NQ][2];
; #pragma unroll
;     for (int q = 0; q < NQ; ++q) {
;         f32x4 (&sq)[4] = s[I0 + q];
;         f32x2_t rs2 = {0.f, 0.f};
; #pragma unroll
;         for (int ss = 0; ss < 4; ++ss) {
; #pragma unroll
;             for (int i = 0; i < 4; ++i) sq[ss][i] = __builtin_amdgcn_exp2f(sq[ss][i]);
;             rs2 += (f32x2_t){sq[ss][0], sq[ss][1]}; rs2 += (f32x2_t){sq[ss][2], sq[ss][3]};
;         }
;         l[I0 + q] += rs2.x + rs2.y;
; #pragma unroll
;         for (int j = 0; j < 2; ++j) {
;             const v4u w = (v4u){cvtpk(sq[2 * j][0], sq[2 * j][1]), cvtpk(sq[2 * j][2], sq[2 * j][3]), cvtpk(sq[2 * j + 1][0], sq[2 * j + 1][1]), cvtpk(sq[2 * j + 1][2], sq[2 * j + 1][3])};
;             pb[q][j] = __builtin_bit_cast(bf16x8, w);
;         }
.Lmla_it0:
	s_cmp_le_u32 s49, s9
	s_cselect_b32 s89, 1, 0
	s_cmp_lt_u32 s49, s9
	s_cselect_b32 s64, 1, 0
	s_add_i32 s96, s49, s21
	s_cmp_lg_u32 s32, s96
	s_cbranch_scc1 .Lmla_nostage0
	s_cmp_gt_u32 s32, s8
	s_cbranch_scc1 .Lmla_nostage0
	v_add_u32_e32 v72, s62, v155
	v_add_u32_e32 v73, s62, v159
	s_waitcnt vmcnt(0)
	ds_write_b128 v72, v[60:63]
	ds_write_b128 v73, v[68:71]
	s_cmp_eq_u32 s63, 0
	s_cbranch_scc1 .Lmla_nok1_10
	v_add_u32_e32 v72, s62, v157
	ds_write_b128 v72, v[64:67]
.Lmla_nok1_10:
	s_add_i32 s32, s32, 1
	s_addk_i32 s62, 0x6800
	s_cmp_lt_u32 s62, 0x13800
	s_cselect_b32 s62, s62, 0
	s_cmp_gt_u32 s32, s8
	s_cbranch_scc1 .Lmla_nostage0
	v_mov_b32_e32 v72, 0x20000
	v_mov_b32_e32 v73, 0
	v_lshl_add_u64 v[160:161], v[160:161], 0, v[72:73]
	v_lshl_add_u64 v[162:163], v[162:163], 0, v[72:73]
	s_nop 0
	global_load_dwordx4 v[60:63], v[160:161], off
	global_load_dwordx4 v[68:71], v[162:163], off
	s_cmp_eq_u32 s63, 0
	s_cbranch_scc1 .Lmla_nostage0
	v_mov_b32_e32 v72, 0x1000
	v_lshl_add_u64 v[166:167], v[166:167], 0, v[72:73]
	s_nop 0
	global_load_dwordx4 v[64:67], v[166:167], off
.Lmla_nostage0:
	s_cmp_eq_u32 s89, 0
	s_cbranch_scc1 .Lmla_bar0
	v_add_u32_e32 v74, s60, v251
	ds_read_b64_tr_b16 v[220:221], v74 offset:16384
	ds_read_b64_tr_b16 v[222:223], v74 offset:18944
	ds_read_b64_tr_b16 v[224:225], v74 offset:21504
	ds_read_b64_tr_b16 v[226:227], v74 offset:24064
	ds_read_b64_tr_b16 v[228:229], v74 offset:16416
	ds_read_b64_tr_b16 v[230:231], v74 offset:18976
	ds_read_b64_tr_b16 v[232:233], v74 offset:21536
	ds_read_b64_tr_b16 v[234:235], v74 offset:24096
	s_cmp_eq_u32 s64, 0
	s_cbranch_scc1 .Lmla_last0
	v_add_u32_e32 v195, s61, v199
	v_add_u32_e32 v196, s61, v201
	v_add_u32_e32 v73, s61, v210
	ds_read_b128 v[236:239], v195
	ds_read_b128 v[240:243], v196
	ds_read_b128 v[244:247], v73
	v_exp_f32_e32 v100, v100
	v_exp_f32_e32 v101, v101
	v_exp_f32_e32 v102, v102
	v_exp_f32_e32 v103, v103
	v_exp_f32_e32 v104, v104
	v_exp_f32_e32 v105, v105
	v_exp_f32_e32 v106, v106
	v_exp_f32_e32 v107, v107
	v_exp_f32_e32 v108, v108
	v_exp_f32_e32 v109, v109
	v_exp_f32_e32 v110, v110
	v_exp_f32_e32 v111, v111
	v_exp_f32_e32 v112, v112
	v_exp_f32_e32 v113, v113
	v_exp_f32_e32 v114, v114
	v_exp_f32_e32 v115, v115
	v_cmp_lt_f32_e64 s[66:67], s77, v200
	v_cmp_lt_f32_e64 s[68:69], s77, v211
	s_nop 1
	v_cndmask_b32_e64 v197, 0, v200, s[66:67]
	v_cndmask_b32_e64 v198, 0, v211, s[68:69]
	v_sub_f32_e32 v204, 0, v197
	v_mov_b32_e32 v205, v204
	v_mov_b32_e32 v206, v204
	v_mov_b32_e32 v207, v204
	v_sub_f32_e32 v252, 0, v198
	v_mov_b32_e32 v253, v252
	v_mov_b32_e32 v254, v252
	v_mov_b32_e32 v255, v252
	s_nop 1
	s_waitcnt lgkmcnt(2)
	v_mfma_f32_16x16x32_bf16 v[24:27], v[236:239], v[0:3], v[204:207]
	v_cvt_pk_bf16_f32 v132, v100, v101
	v_cvt_pk_bf16_f32 v133, v102, v103
	v_mfma_f32_16x16x32_bf16 v[40:43], v[236:239], v[12:15], v[252:255]
	v_cvt_pk_bf16_f32 v134, v104, v105
	v_cvt_pk_bf16_f32 v135, v106, v107
	ds_read_b128 v[236:239], v195 offset:4096
	s_waitcnt lgkmcnt(2)
	v_mfma_f32_16x16x32_bf16 v[24:27], v[240:243], v[4:7], v[24:27]
	v_cvt_pk_bf16_f32 v136, v108, v109
	v_cvt_pk_bf16_f32 v137, v110, v111
	v_mfma_f32_16x16x32_bf16 v[40:43], v[240:243], v[16:19], v[40:43]
	v_cvt_pk_bf16_f32 v138, v112, v113
	v_cvt_pk_bf16_f32 v139, v114, v115
	ds_read_b128 v[240:243], v196 offset:4096
	s_waitcnt lgkmcnt(2)
	v_mfma_f32_16x16x32_bf16 v[24:27], v[244:247], v[8:11], v[24:27]
	v_exp_f32_e32 v116, v116
	v_mfma_f32_16x16x32_bf16 v[40:43], v[244:247], v[20:23], v[40:43]
	v_exp_f32_e32 v117, v117
	ds_read_b128 v[244:247], v73 offset:4096
	s_waitcnt lgkmcnt(2)
	v_mfma_f32_16x16x32_bf16 v[28:31], v[236:239], v[0:3], v[204:207]
	v_exp_f32_e32 v118, v118
	v_mfma_f32_16x16x32_bf16 v[44:47], v[236:239], v[12:15], v[252:255]
	v_exp_f32_e32 v119, v119
	ds_read_b128 v[236:239], v195 offset:8192
	s_waitcnt lgkmcnt(2)
	v_mfma_f32_16x16x32_bf16 v[28:31], v[240:243], v[4:7], v[28:31]
	v_exp_f32_e32 v120, v120
	v_mfma_f32_16x16x32_bf16 v[44:47], v[240:243], v[16:19], v[44:47]
	v_exp_f32_e32 v121, v121
	ds_read_b128 v[240:243], v196 offset:8192
	s_waitcnt lgkmcnt(2)
	v_mfma_f32_16x16x32_bf16 v[28:31], v[244:247], v[8:11], v[28:31]
	v_exp_f32_e32 v122, v122
	v_mfma_f32_16x16x32_bf16 v[44:47], v[244:247], v[20:23], v[44:47]
	v_exp_f32_e32 v123, v123
	ds_read_b128 v[244:247], v73 offset:8192
	s_waitcnt lgkmcnt(2)
	v_mfma_f32_16x16x32_bf16 v[32:35], v[236:239], v[0:3], v[204:207]
	v_exp_f32_e32 v124, v124
	v_mfma_f32_16x16x32_bf16 v[212:215], v[236:239], v[12:15], v[252:255]
	v_exp_f32_e32 v125, v125
	ds_read_b128 v[236:239], v195 offset:12288
	s_waitcnt lgkmcnt(2)
; #define LAS __attribute__((address_space(3)))
; __device__ __forceinline__ unsigned cvtpk(float lo, float hi) { f32x2_t v = {lo, hi}; bf16x2_t b = __builtin_convertvector(v, bf16x2_t); return __builtin_bit_cast(unsigned, b); }
; template <int I0, int NQ, int VO> __device__ __forceinline__ void tile_y(LAS unsigned char* lds, float (&l)[2], f32x4 (&o)[2][4], f32x4 (&s)[2][4], int fr, int fq) {
;     bf16x8 pb[NQ][2];
; #pragma unroll
;     for (int q = 0; q < NQ; ++q) {
;         f32x4 (&sq)[4] = s[I0 + q];
;         f32x2_t rs2 = {0.f, 0.f};
; #pragma unroll
;         for (int ss = 0; ss < 4; ++ss) {
; #pragma unroll
;             for (int i = 0; i < 4; ++i) sq[ss][i] = __builtin_amdgcn_exp2f(sq[ss][i]);
;             rs2 += (f32x2_t){sq[ss][0], sq[ss][1]}; rs2 += (f32x2_t){sq[ss][2], sq[ss][3]};
;         }
;         l[I0 + q] += rs2.x + rs2.y;
; #pragma unroll
;         for (int j = 0; j < 2; ++j) {
;             const v4u w = (v4u){cvtpk(sq[2 * j][0], sq[2 * j][1]), cvtpk(sq[2 * j][2], sq[2 * j][3]), cvtpk(sq[2 * j + 1][0], sq[2 * j + 1][1]), cvtpk(sq[2 * j + 1][2], sq[2 * j + 1][3])};
;             pb[q][j] = __builtin_bit_cast(bf16x8, w);
;         }
;     }
; #pragma unroll
;     for (int dt = 0; dt < 4; ++dt)
; #pragma unroll
;         for (int j = 0; j < 2; ++j) {
;             LAS unsigned char* vp = lds + VO + ((32 * j + 4 * fq + (fr >> 2)) * VSTR + 16 * dt + 4 * (fr & 3)) * 2;
;             const s16x4 lo = __builtin_bit_cast(s16x4, __builtin_amdgcn_ds_read_tr16_b64_v4i16((LAS v4i16_t*)vp));
;             const s16x4 hi = __builtin_bit_cast(s16x4, __builtin_amdgcn_ds_read_tr16_b64_v4i16((LAS v4i16_t*)(vp + 16 * VSTR * 2)));
;             const bf16x8 vf = (bf16x8){lo[0], lo[1], lo[2], lo[3], hi[0], hi[1], hi[2], hi[3]};
; #pragma unroll
;             for (int q = 0; q < NQ; ++q) o[I0 + q][dt] = __builtin_amdgcn_mfma_f32_16x16x32_bf16(vf, pb[q][j], o[I0 + q][dt], 0, 0, 0);
;         }
	v_mfma_f32_16x16x32_bf16 v[32:35], v[240:243], v[4:7], v[32:35]
	v_exp_f32_e32 v126, v126
	v_mfma_f32_16x16x32_bf16 v[212:215], v[240:243], v[16:19], v[212:215]
	v_exp_f32_e32 v127, v127
	ds_read_b128 v[240:243], v196 offset:12288
	s_waitcnt lgkmcnt(2)
	v_mfma_f32_16x16x32_bf16 v[32:35], v[244:247], v[8:11], v[32:35]
	v_exp_f32_e32 v128, v128
	v_mfma_f32_16x16x32_bf16 v[212:215], v[244:247], v[20:23], v[212:215]
	v_exp_f32_e32 v129, v129
	ds_read_b128 v[244:247], v73 offset:12288
	s_waitcnt lgkmcnt(2)
	v_mfma_f32_16x16x32_bf16 v[36:39], v[236:239], v[0:3], v[204:207]
	v_exp_f32_e32 v130, v130
	v_mfma_f32_16x16x32_bf16 v[216:219], v[236:239], v[12:15], v[252:255]
	v_exp_f32_e32 v131, v131
	ds_read_b64_tr_b16 v[236:237], v74 offset:16448
	ds_read_b64_tr_b16 v[238:239], v74 offset:19008
	s_waitcnt lgkmcnt(3)
	v_mfma_f32_16x16x32_bf16 v[36:39], v[240:243], v[4:7], v[36:39]
	v_cvt_pk_bf16_f32 v140, v116, v117
	v_cvt_pk_bf16_f32 v141, v118, v119
	v_mfma_f32_16x16x32_bf16 v[216:219], v[240:243], v[16:19], v[216:219]
	v_cvt_pk_bf16_f32 v142, v120, v121
	v_cvt_pk_bf16_f32 v143, v122, v123
	ds_read_b64_tr_b16 v[240:241], v74 offset:21568
	ds_read_b64_tr_b16 v[242:243], v74 offset:24128
	s_waitcnt lgkmcnt(4)
	v_mfma_f32_16x16x32_bf16 v[36:39], v[244:247], v[8:11], v[36:39]
	v_cvt_pk_bf16_f32 v52, v124, v125
	v_cvt_pk_bf16_f32 v53, v126, v127
	v_mfma_f32_16x16x32_bf16 v[216:219], v[244:247], v[20:23], v[216:219]
	v_cvt_pk_bf16_f32 v54, v128, v129
	v_cvt_pk_bf16_f32 v55, v130, v131
	ds_read_b64_tr_b16 v[244:245], v74 offset:16480
	ds_read_b64_tr_b16 v[246:247], v74 offset:19040
	ds_read_b64_tr_b16 v[204:205], v74 offset:21600
	ds_read_b64_tr_b16 v[206:207], v74 offset:24160
	s_waitcnt lgkmcnt(15)
	v_mfma_f32_16x16x32_bf16 v[96:99], v[220:223], v[132:135], v[96:99]
	v_add_f32_e32 v100, v100, v101
	v_add_f32_e32 v102, v102, v103
	v_mfma_f32_16x16x32_bf16 v[84:87], v[220:223], v[140:143], v[84:87]
	v_add_f32_e32 v104, v104, v105
	v_add_f32_e32 v106, v106, v107
	s_waitcnt lgkmcnt(15)
	v_mfma_f32_16x16x32_bf16 v[96:99], v[224:227], v[136:139], v[96:99]
	v_add_f32_e32 v108, v108, v109
	v_add_f32_e32 v110, v110, v111
	v_mfma_f32_16x16x32_bf16 v[84:87], v[224:227], v[52:55], v[84:87]
	v_add_f32_e32 v112, v112, v113
	v_add_f32_e32 v114, v114, v115
	s_waitcnt lgkmcnt(15)
	v_mfma_f32_16x16x32_bf16 v[88:91], v[228:231], v[132:135], v[88:91]
	v_add_f32_e32 v100, v100, v102
	v_add_f32_e32 v104, v104, v106
	v_mfma_f32_16x16x32_bf16 v[76:79], v[228:231], v[140:143], v[76:79]
	v_add_f32_e32 v108, v108, v110
	v_add_f32_e32 v112, v112, v114
	s_waitcnt lgkmcnt(15)
	v_mfma_f32_16x16x32_bf16 v[88:91], v[232:235], v[136:139], v[88:91]
	v_add_f32_e32 v100, v100, v104
	v_add_f32_e32 v108, v108, v112
	v_mfma_f32_16x16x32_bf16 v[76:79], v[232:235], v[52:55], v[76:79]
	v_add_f32_e32 v100, v100, v108
	v_add_f32_e32 v165, v165, v100
	s_waitcnt lgkmcnt(6)
	v_mfma_f32_16x16x32_bf16 v[92:95], v[236:239], v[132:135], v[92:95]
	v_add_f32_e32 v116, v116, v117
	v_add_f32_e32 v118, v118, v119
	v_mfma_f32_16x16x32_bf16 v[80:83], v[236:239], v[140:143], v[80:83]
	v_add_f32_e32 v120, v120, v121
	v_add_f32_e32 v122, v122, v123
	s_waitcnt lgkmcnt(4)
	v_mfma_f32_16x16x32_bf16 v[92:95], v[240:243], v[136:139], v[92:95]
	v_add_f32_e32 v124, v124, v125
	v_add_f32_e32 v126, v126, v127
	v_mfma_f32_16x16x32_bf16 v[80:83], v[240:243], v[52:55], v[80:83]
	v_add_f32_e32 v128, v128, v129
	v_add_f32_e32 v130, v130, v131
	s_waitcnt lgkmcnt(2)
	v_mfma_f32_16x16x32_bf16 v[48:51], v[244:247], v[132:135], v[48:51]
	v_add_f32_e32 v116, v116, v118
	v_add_f32_e32 v120, v120, v122
	v_mfma_f32_16x16x32_bf16 v[56:59], v[244:247], v[140:143], v[56:59]
	v_add_f32_e32 v124, v124, v126
	v_add_f32_e32 v128, v128, v130
	s_waitcnt lgkmcnt(0)
	v_mfma_f32_16x16x32_bf16 v[48:51], v[204:207], v[136:139], v[48:51]
	v_add_f32_e32 v116, v116, v120
	v_add_f32_e32 v124, v124, v128
	v_mfma_f32_16x16x32_bf16 v[56:59], v[204:207], v[52:55], v[56:59]
	v_add_f32_e32 v116, v116, v124
	v_add_f32_e32 v164, v164, v116
	s_add_i32 s65, s49, 1
	s_cmp_eq_u32 s65, s9
	s_cbranch_scc1 .Lmla_mask0
.Lmla_chk0:
	v_max_i32_e32 v72, v24, v28
	v_max3_i32 v72, v32, v36, v72
	v_cmp_lt_i32_e32 vcc, s80, v72
	s_orn2_b64 vcc, vcc, s[66:67]
	s_cbranch_vccnz .Lmla_slow0_0
.Lmla_chk0_1:
	v_max_i32_e32 v72, v40, v44
	v_max3_i32 v72, v212, v216, v72
	v_cmp_lt_i32_e32 vcc, s80, v72
	s_orn2_b64 vcc, vcc, s[68:69]
	s_cbranch_vccnz .Lmla_slow0_1
.Lmla_bar0:
	s_waitcnt lgkmcnt(0)
	s_barrier
	s_add_i32 s49, s49, 1
	s_mov_b32 s60, s61
	s_addk_i32 s61, 0x6800
	s_cmp_lt_u32 s61, 0x13800
	s_cselect_b32 s61, s61, 0
	s_cmp_le_u32 s49, s8
	s_cbranch_scc1 .Lmla_it1
	s_branch .Lmla_exit

; #define LAS __attribute__((address_space(3)))
; __device__ __forceinline__ unsigned cvtpk(float lo, float hi) { f32x2_t v = {lo, hi}; bf16x2_t b = __builtin_convertvector(v, bf16x2_t); return __builtin_bit_cast(unsigned, b); }
; template <int I0, int NQ, int VO> __device__ __forceinline__ void tile_y(LAS unsigned char* lds, float (&l)[2], f32x4 (&o)[2][4], f32x4 (&s)[2][4], int fr, int fq) {
;     bf16x8 pb[NQ][2];
; #pragma unroll
;     for (int q = 0; q < NQ; ++q) {
;         f32x4 (&sq)[4] = s[I0 + q];
;         f32x2_t rs2 = {0.f, 0.f};
; #pragma unroll
;         for (int ss = 0; ss < 4; ++ss) {
; #pragma unroll
;             for (int i = 0; i < 4; ++i) sq[ss][i] = __builtin_amdgcn_exp2f(sq[ss][i]);
;             rs2 += (f32x2_t){sq[ss][0], sq[ss][1]}; rs2 += (f32x2_t){sq[ss][2], sq[ss][3]};
;         }
;         l[I0 + q] += rs2.x + rs2.y;
; #pragma unroll
;         for (int j = 0; j < 2; ++j) {
;             const v4u w = (v4u){cvtpk(sq[2 * j][0], sq[2 * j][1]), cvtpk(sq[2 * j][2], sq[2 * j][3]), cvtpk(sq[2 * j + 1][0], sq[2 * j + 1][1]), cvtpk(sq[2 * j + 1][2], sq[2 * j + 1][3])};
;             pb[q][j] = __builtin_bit_cast(bf16x8, w);
;         }
; template <int DQK> __device__ __forceinline__ void x1_tile(LAS unsigned char* lds, const bf16x8 (&qf)[2][DQK / 32], const float (&m)[2], f32x4 (&s)[2][4], int fr, int fq) {
;     constexpr int NKS = DQK / 32;
; #pragma unroll
;     for (int q = 0; q < 2; ++q) { const float c = (m[q] > -1e29f) ? -m[q] : 0.f;
; #pragma unroll
;         for (int ss = 0; ss < 4; ++ss) s[q][ss] = (f32x4){c, c, c, c}; }
; #pragma unroll
;     for (int ss = 0; ss < 4; ++ss)
; #pragma unroll
;         for (int ks = 0; ks < NKS; ++ks) {
;             const bf16x8 kf = *(const LAS bf16x8*)(lds + k_off<DQK>(16 * ss + fr, 4 * ks + fq));
; #pragma unroll
;             for (int q = 0; q < 2; ++q) s[q][ss] = __builtin_amdgcn_mfma_f32_16x16x32_bf16(kf, qf[q][ks], s[q][ss], 0, 0, 0);
;         }
; }
.Lmla_nostage1:
	s_cmp_eq_u32 s89, 0
	s_cbranch_scc1 .Lmla_bar1
	v_add_u32_e32 v74, s60, v251
	ds_read_b64_tr_b16 v[220:221], v74 offset:16384
	ds_read_b64_tr_b16 v[222:223], v74 offset:18944
	ds_read_b64_tr_b16 v[224:225], v74 offset:21504
	ds_read_b64_tr_b16 v[226:227], v74 offset:24064
	ds_read_b64_tr_b16 v[228:229], v74 offset:16416
	ds_read_b64_tr_b16 v[230:231], v74 offset:18976
	ds_read_b64_tr_b16 v[232:233], v74 offset:21536
	ds_read_b64_tr_b16 v[234:235], v74 offset:24096
	s_cmp_eq_u32 s64, 0
	s_cbranch_scc1 .Lmla_last1
	v_add_u32_e32 v195, s61, v199
	v_add_u32_e32 v196, s61, v201
	v_add_u32_e32 v73, s61, v210
	ds_read_b128 v[236:239], v195
	ds_read_b128 v[240:243], v196
	ds_read_b128 v[244:247], v73
	v_exp_f32_e32 v24, v24
	v_exp_f32_e32 v25, v25
	v_exp_f32_e32 v26, v26
	v_exp_f32_e32 v27, v27
	v_exp_f32_e32 v28, v28
	v_exp_f32_e32 v29, v29
	v_exp_f32_e32 v30, v30
	v_exp_f32_e32 v31, v31
	v_exp_f32_e32 v32, v32
	v_exp_f32_e32 v33, v33
	v_exp_f32_e32 v34, v34
	v_exp_f32_e32 v35, v35
	v_exp_f32_e32 v36, v36
	v_exp_f32_e32 v37, v37
	v_exp_f32_e32 v38, v38
	v_exp_f32_e32 v39, v39
	v_cmp_lt_f32_e64 s[66:67], s77, v200
	v_cmp_lt_f32_e64 s[68:69], s77, v211
	s_nop 1
	v_cndmask_b32_e64 v197, 0, v200, s[66:67]
	v_cndmask_b32_e64 v198, 0, v211, s[68:69]
	v_sub_f32_e32 v204, 0, v197
	v_mov_b32_e32 v205, v204
	v_mov_b32_e32 v206, v204
	v_mov_b32_e32 v207, v204
	v_sub_f32_e32 v252, 0, v198
	v_mov_b32_e32 v253, v252
	v_mov_b32_e32 v254, v252
	v_mov_b32_e32 v255, v252
	s_nop 1
	s_waitcnt lgkmcnt(2)
	v_mfma_f32_16x16x32_bf16 v[100:103], v[236:239], v[0:3], v[204:207]
	v_cvt_pk_bf16_f32 v132, v24, v25
	v_cvt_pk_bf16_f32 v133, v26, v27
	v_mfma_f32_16x16x32_bf16 v[116:119], v[236:239], v[12:15], v[252:255]
	v_cvt_pk_bf16_f32 v134, v28, v29
	v_cvt_pk_bf16_f32 v135, v30, v31
	ds_read_b128 v[236:239], v195 offset:4096
	s_waitcnt lgkmcnt(2)
	v_mfma_f32_16x16x32_bf16 v[100:103], v[240:243], v[4:7], v[100:103]
	v_cvt_pk_bf16_f32 v136, v32, v33
	v_cvt_pk_bf16_f32 v137, v34, v35
	v_mfma_f32_16x16x32_bf16 v[116:119], v[240:243], v[16:19], v[116:119]
	v_cvt_pk_bf16_f32 v138, v36, v37
	v_cvt_pk_bf16_f32 v139, v38, v39
	ds_read_b128 v[240:243], v196 offset:4096
	s_waitcnt lgkmcnt(2)
	v_mfma_f32_16x16x32_bf16 v[100:103], v[244:247], v[8:11], v[100:103]
	v_exp_f32_e32 v40, v40
	v_mfma_f32_16x16x32_bf16 v[116:119], v[244:247], v[20:23], v[116:119]
	v_exp_f32_e32 v41, v41
	ds_read_b128 v[244:247], v73 offset:4096
	s_waitcnt lgkmcnt(2)
	v_mfma_f32_16x16x32_bf16 v[104:107], v[236:239], v[0:3], v[204:207]
	v_exp_f32_e32 v42, v42
	v_mfma_f32_16x16x32_bf16 v[120:123], v[236:239], v[12:15], v[252:255]
	v_exp_f32_e32 v43, v43
	ds_read_b128 v[236:239], v195 offset:8192
	s_waitcnt lgkmcnt(2)
	v_mfma_f32_16x16x32_bf16 v[104:107], v[240:243], v[4:7], v[104:107]
	v_exp_f32_e32 v44, v44
	v_mfma_f32_16x16x32_bf16 v[120:123], v[240:243], v[16:19], v[120:123]
	v_exp_f32_e32 v45, v45
	ds_read_b128 v[240:243], v196 offset:8192
	s_waitcnt lgkmcnt(2)
	v_mfma_f32_16x16x32_bf16 v[104:107], v[244:247], v[8:11], v[104:107]
	v_exp_f32_e32 v46, v46
	v_mfma_f32_16x16x32_bf16 v[120:123], v[244:247], v[20:23], v[120:123]
	v_exp_f32_e32 v47, v47
	ds_read_b128 v[244:247], v73 offset:8192
	s_waitcnt lgkmcnt(2)
	v_mfma_f32_16x16x32_bf16 v[108:111], v[236:239], v[0:3], v[204:207]
	v_exp_f32_e32 v212, v212
	v_mfma_f32_16x16x32_bf16 v[124:127], v[236:239], v[12:15], v[252:255]
	v_exp_f32_e32 v213, v213
	ds_read_b128 v[236:239], v195 offset:12288
	s_waitcnt lgkmcnt(2)
	v_mfma_f32_16x16x32_bf16 v[108:111], v[240:243], v[4:7], v[108:111]
	v_exp_f32_e32 v214, v214
	v_mfma_f32_16x16x32_bf16 v[124:127], v[240:243], v[16:19], v[124:127]
	v_exp_f32_e32 v215, v215
	ds_read_b128 v[240:243], v196 offset:12288
	s_waitcnt lgkmcnt(2)
	v_mfma_f32_16x16x32_bf16 v[108:111], v[244:247], v[8:11], v[108:111]
	v_exp_f32_e32 v216, v216
	v_mfma_f32_16x16x32_bf16 v[124:127], v[244:247], v[20:23], v[124:127]
	v_exp_f32_e32 v217, v217
	ds_read_b128 v[244:247], v73 offset:12288
	s_waitcnt lgkmcnt(2)
; #define LAS __attribute__((address_space(3)))
; #define IMX3(a, b, c) imax2(imax2((a), __builtin_bit_cast(int, (b))), __builtin_bit_cast(int, (c)))
; #define IMX3(a, b, c) imax2(imax2((a), __builtin_bit_cast(int, (b))), __builtin_bit_cast(int, (c)))
; template <int I0, int NQ, int VO> __device__ __forceinline__ void tile_y(LAS unsigned char* lds, float (&l)[2], f32x4 (&o)[2][4], f32x4 (&s)[2][4], int fr, int fq) {
;     ...
; #pragma unroll
;     for (int dt = 0; dt < 4; ++dt)
; #pragma unroll
;         for (int j = 0; j < 2; ++j) {
;             LAS unsigned char* vp = lds + VO + ((32 * j + 4 * fq + (fr >> 2)) * VSTR + 16 * dt + 4 * (fr & 3)) * 2;
;             const s16x4 lo = __builtin_bit_cast(s16x4, __builtin_amdgcn_ds_read_tr16_b64_v4i16((LAS v4i16_t*)vp));
;             const s16x4 hi = __builtin_bit_cast(s16x4, __builtin_amdgcn_ds_read_tr16_b64_v4i16((LAS v4i16_t*)(vp + 16 * VSTR * 2)));
;             const bf16x8 vf = (bf16x8){lo[0], lo[1], lo[2], lo[3], hi[0], hi[1], hi[2], hi[3]};
; #pragma unroll
;             for (int q = 0; q < NQ; ++q) o[I0 + q][dt] = __builtin_amdgcn_mfma_f32_16x16x32_bf16(vf, pb[q][j], o[I0 + q][dt], 0, 0, 0);
;         }
; template <bool FULL> __device__ __forceinline__ void x2_tile(int kbase, const int (&tpos)[2], float (&m)[2], float (&l)[2], f32x4 (&o)[2][4], f32x4 (&s)[2][4], int fq) {
;     ...
;         if (FULL) {
;             int ia = __builtin_bit_cast(int, sq[0][0]);
;     ...
;             ia = IMX3(ia, sq[0][1], sq[0][2]); ia = IMX3(ia, sq[0][3], sq[1][0]); ia = IMX3(ia, sq[1][1], sq[1][2]); ia = IMX3(ia, sq[1][3], sq[2][0]);
;             int ib = __builtin_bit_cast(int, sq[2][1]);
;             ib = IMX3(ib, sq[2][2], sq[2][3]); ib = IMX3(ib, sq[3][0], sq[3][1]); ib = IMX3(ib, sq[3][2], sq[3][3]);
;     ...
;             const bool big = !(mo > -1e29f) || (imax2(ia, ib) > __builtin_bit_cast(int, RESCALE_THR));
;             slow = __any(big ? 1 : 0) != 0;
;         }
	v_mfma_f32_16x16x32_bf16 v[112:115], v[236:239], v[0:3], v[204:207]
	v_exp_f32_e32 v218, v218
	v_mfma_f32_16x16x32_bf16 v[128:131], v[236:239], v[12:15], v[252:255]
	v_exp_f32_e32 v219, v219
	ds_read_b64_tr_b16 v[236:237], v74 offset:16448
	ds_read_b64_tr_b16 v[238:239], v74 offset:19008
	s_waitcnt lgkmcnt(3)
	v_mfma_f32_16x16x32_bf16 v[112:115], v[240:243], v[4:7], v[112:115]
	v_cvt_pk_bf16_f32 v140, v40, v41
	v_cvt_pk_bf16_f32 v141, v42, v43
	v_mfma_f32_16x16x32_bf16 v[128:131], v[240:243], v[16:19], v[128:131]
	v_cvt_pk_bf16_f32 v142, v44, v45
	v_cvt_pk_bf16_f32 v143, v46, v47
	ds_read_b64_tr_b16 v[240:241], v74 offset:21568
	ds_read_b64_tr_b16 v[242:243], v74 offset:24128
	s_waitcnt lgkmcnt(4)
	v_mfma_f32_16x16x32_bf16 v[112:115], v[244:247], v[8:11], v[112:115]
	v_cvt_pk_bf16_f32 v52, v212, v213
	v_cvt_pk_bf16_f32 v53, v214, v215
	v_mfma_f32_16x16x32_bf16 v[128:131], v[244:247], v[20:23], v[128:131]
	v_cvt_pk_bf16_f32 v54, v216, v217
	v_cvt_pk_bf16_f32 v55, v218, v219
	ds_read_b64_tr_b16 v[244:245], v74 offset:16480
	ds_read_b64_tr_b16 v[246:247], v74 offset:19040
	ds_read_b64_tr_b16 v[204:205], v74 offset:21600
	ds_read_b64_tr_b16 v[206:207], v74 offset:24160
	s_waitcnt lgkmcnt(15)
	v_mfma_f32_16x16x32_bf16 v[96:99], v[220:223], v[132:135], v[96:99]
	v_add_f32_e32 v24, v24, v25
	v_add_f32_e32 v26, v26, v27
	v_mfma_f32_16x16x32_bf16 v[84:87], v[220:223], v[140:143], v[84:87]
	v_add_f32_e32 v28, v28, v29
	v_add_f32_e32 v30, v30, v31
	s_waitcnt lgkmcnt(15)
	v_mfma_f32_16x16x32_bf16 v[96:99], v[224:227], v[136:139], v[96:99]
	v_add_f32_e32 v32, v32, v33
	v_add_f32_e32 v34, v34, v35
	v_mfma_f32_16x16x32_bf16 v[84:87], v[224:227], v[52:55], v[84:87]
	v_add_f32_e32 v36, v36, v37
	v_add_f32_e32 v38, v38, v39
	s_waitcnt lgkmcnt(15)
	v_mfma_f32_16x16x32_bf16 v[88:91], v[228:231], v[132:135], v[88:91]
	v_add_f32_e32 v24, v24, v26
	v_add_f32_e32 v28, v28, v30
	v_mfma_f32_16x16x32_bf16 v[76:79], v[228:231], v[140:143], v[76:79]
	v_add_f32_e32 v32, v32, v34
	v_add_f32_e32 v36, v36, v38
	s_waitcnt lgkmcnt(15)
	v_mfma_f32_16x16x32_bf16 v[88:91], v[232:235], v[136:139], v[88:91]
	v_add_f32_e32 v24, v24, v28
	v_add_f32_e32 v32, v32, v36
	v_mfma_f32_16x16x32_bf16 v[76:79], v[232:235], v[52:55], v[76:79]
	v_add_f32_e32 v24, v24, v32
	v_add_f32_e32 v165, v165, v24
	s_waitcnt lgkmcnt(6)
	v_mfma_f32_16x16x32_bf16 v[92:95], v[236:239], v[132:135], v[92:95]
	v_add_f32_e32 v40, v40, v41
	v_add_f32_e32 v42, v42, v43
	v_mfma_f32_16x16x32_bf16 v[80:83], v[236:239], v[140:143], v[80:83]
	v_add_f32_e32 v44, v44, v45
	v_add_f32_e32 v46, v46, v47
	s_waitcnt lgkmcnt(4)
	v_mfma_f32_16x16x32_bf16 v[92:95], v[240:243], v[136:139], v[92:95]
	v_add_f32_e32 v212, v212, v213
	v_add_f32_e32 v214, v214, v215
	v_mfma_f32_16x16x32_bf16 v[80:83], v[240:243], v[52:55], v[80:83]
	v_add_f32_e32 v216, v216, v217
	v_add_f32_e32 v218, v218, v219
	s_waitcnt lgkmcnt(2)
	v_mfma_f32_16x16x32_bf16 v[48:51], v[244:247], v[132:135], v[48:51]
	v_add_f32_e32 v40, v40, v42
	v_add_f32_e32 v44, v44, v46
	v_mfma_f32_16x16x32_bf16 v[56:59], v[244:247], v[140:143], v[56:59]
	v_add_f32_e32 v212, v212, v214
	v_add_f32_e32 v216, v216, v218
	s_waitcnt lgkmcnt(0)
	v_mfma_f32_16x16x32_bf16 v[48:51], v[204:207], v[136:139], v[48:51]
	v_add_f32_e32 v40, v40, v44
	v_add_f32_e32 v212, v212, v216
	v_mfma_f32_16x16x32_bf16 v[56:59], v[204:207], v[52:55], v[56:59]
	v_add_f32_e32 v40, v40, v212
	v_add_f32_e32 v164, v164, v40
	s_add_i32 s65, s49, 1
	s_cmp_eq_u32 s65, s9
	s_cbranch_scc1 .Lmla_mask1
.Lmla_chk1:
	v_max_i32_e32 v72, v100, v104
	v_max3_i32 v72, v108, v112, v72
	v_cmp_lt_i32_e32 vcc, s80, v72
	s_orn2_b64 vcc, vcc, s[66:67]
	s_cbranch_vccnz .Lmla_slow1_0
.Lmla_chk1_1:
	v_max_i32_e32 v72, v116, v120
	v_max3_i32 v72, v124, v128, v72
	v_cmp_lt_i32_e32 vcc, s80, v72
	s_orn2_b64 vcc, vcc, s[68:69]
	s_cbranch_vccnz .Lmla_slow1_1

; #define LAS __attribute__((address_space(3)))
; template <int I0, int NQ, int VO> __device__ __forceinline__ void tile_y(LAS unsigned char* lds, float (&l)[2], f32x4 (&o)[2][4], f32x4 (&s)[2][4], int fr, int fq) {
;     bf16x8 pb[NQ][2];
; #pragma unroll
;     for (int q = 0; q < NQ; ++q) {
;         f32x4 (&sq)[4] = s[I0 + q];
;         f32x2_t rs2 = {0.f, 0.f};
; #pragma unroll
;         for (int ss = 0; ss < 4; ++ss) {
; #pragma unroll
;             for (int i = 0; i < 4; ++i) sq[ss][i] = __builtin_amdgcn_exp2f(sq[ss][i]);
;             rs2 += (f32x2_t){sq[ss][0], sq[ss][1]}; rs2 += (f32x2_t){sq[ss][2], sq[ss][3]};
;         }
;         l[I0 + q] += rs2.x + rs2.y;
; #pragma unroll
;         for (int j = 0; j < 2; ++j) {
;             const v4u w = (v4u){cvtpk(sq[2 * j][0], sq[2 * j][1]), cvtpk(sq[2 * j][2], sq[2 * j][3]), cvtpk(sq[2 * j + 1][0], sq[2 * j + 1][1]), cvtpk(sq[2 * j + 1][2], sq[2 * j + 1][3])};
;             pb[q][j] = __builtin_bit_cast(bf16x8, w);
;         }
;     }
; #pragma unroll
;     for (int dt = 0; dt < 4; ++dt)
; #pragma unroll
;         for (int j = 0; j < 2; ++j) {
;             LAS unsigned char* vp = lds + VO + ((32 * j + 4 * fq + (fr >> 2)) * VSTR + 16 * dt + 4 * (fr & 3)) * 2;
;             const s16x4 lo = __builtin_bit_cast(s16x4, __builtin_amdgcn_ds_read_tr16_b64_v4i16((LAS v4i16_t*)vp));
;             const s16x4 hi = __builtin_bit_cast(s16x4, __builtin_amdgcn_ds_read_tr16_b64_v4i16((LAS v4i16_t*)(vp + 16 * VSTR * 2)));
;             const bf16x8 vf = (bf16x8){lo[0], lo[1], lo[2], lo[3], hi[0], hi[1], hi[2], hi[3]};
; #pragma unroll
;             for (int q = 0; q < NQ; ++q) o[I0 + q][dt] = __builtin_amdgcn_mfma_f32_16x16x32_bf16(vf, pb[q][j], o[I0 + q][dt], 0, 0, 0);
;         }
; template <bool FULL> __device__ __forceinline__ void x2_tile(int kbase, const int (&tpos)[2], float (&m)[2], float (&l)[2], f32x4 (&o)[2][4], f32x4 (&s)[2][4], int fq) {
;     ...
;                 mx = fmaxf(fmaxf(sq[0][0], sq[0][1]), fmaxf(sq[0][2], sq[0][3]));
; #pragma unroll
;                 for (int ss = 1; ss < 4; ++ss) mx = fmaxf(mx, fmaxf(fmaxf(sq[ss][0], sq[ss][1]), fmaxf(sq[ss][2], sq[ss][3])));
;             } else {
;                 mx = NEG;
; #pragma unroll
;                 for (int ss = 0; ss < 4; ++ss)
; #pragma unroll
.Lmla_last0:
	v_add_u32_e32 v74, s60, v251
	ds_read_b64_tr_b16 v[236:237], v74 offset:16448
	ds_read_b64_tr_b16 v[238:239], v74 offset:19008
	ds_read_b64_tr_b16 v[240:241], v74 offset:21568
	ds_read_b64_tr_b16 v[242:243], v74 offset:24128
	ds_read_b64_tr_b16 v[244:245], v74 offset:16480
	ds_read_b64_tr_b16 v[246:247], v74 offset:19040
	ds_read_b64_tr_b16 v[204:205], v74 offset:21600
	ds_read_b64_tr_b16 v[206:207], v74 offset:24160
	v_exp_f32_e32 v100, v100
	v_exp_f32_e32 v101, v101
	v_exp_f32_e32 v102, v102
	v_exp_f32_e32 v103, v103
	v_exp_f32_e32 v104, v104
	v_exp_f32_e32 v105, v105
	v_exp_f32_e32 v106, v106
	v_exp_f32_e32 v107, v107
	v_exp_f32_e32 v108, v108
	v_exp_f32_e32 v109, v109
	v_exp_f32_e32 v110, v110
	v_exp_f32_e32 v111, v111
	v_exp_f32_e32 v112, v112
	v_exp_f32_e32 v113, v113
	v_exp_f32_e32 v114, v114
	v_exp_f32_e32 v115, v115
	v_cvt_pk_bf16_f32 v132, v100, v101
	v_cvt_pk_bf16_f32 v133, v102, v103
	v_cvt_pk_bf16_f32 v134, v104, v105
	v_cvt_pk_bf16_f32 v135, v106, v107
	v_cvt_pk_bf16_f32 v136, v108, v109
	v_cvt_pk_bf16_f32 v137, v110, v111
	v_cvt_pk_bf16_f32 v138, v112, v113
	v_cvt_pk_bf16_f32 v139, v114, v115
	v_add_f32_e32 v100, v100, v101
	v_add_f32_e32 v102, v102, v103
	v_add_f32_e32 v104, v104, v105
	v_add_f32_e32 v106, v106, v107
	v_add_f32_e32 v108, v108, v109
	v_add_f32_e32 v110, v110, v111
	v_add_f32_e32 v112, v112, v113
	v_add_f32_e32 v114, v114, v115
	v_add_f32_e32 v100, v100, v102
	v_add_f32_e32 v104, v104, v106
	v_add_f32_e32 v108, v108, v110
	v_add_f32_e32 v112, v112, v114
	v_add_f32_e32 v100, v100, v104
	v_add_f32_e32 v108, v108, v112
	v_add_f32_e32 v100, v100, v108
	v_add_f32_e32 v165, v165, v100
	v_exp_f32_e32 v116, v116
	v_exp_f32_e32 v117, v117
	v_exp_f32_e32 v118, v118
	v_exp_f32_e32 v119, v119
	v_exp_f32_e32 v120, v120
	v_exp_f32_e32 v121, v121
	v_exp_f32_e32 v122, v122
	v_exp_f32_e32 v123, v123
	v_exp_f32_e32 v124, v124
	v_exp_f32_e32 v125, v125
	v_exp_f32_e32 v126, v126
	v_exp_f32_e32 v127, v127
	v_exp_f32_e32 v128, v128
	v_exp_f32_e32 v129, v129
	v_exp_f32_e32 v130, v130
	v_exp_f32_e32 v131, v131
	v_cvt_pk_bf16_f32 v140, v116, v117
	v_cvt_pk_bf16_f32 v141, v118, v119
	v_cvt_pk_bf16_f32 v142, v120, v121
	v_cvt_pk_bf16_f32 v143, v122, v123
	v_cvt_pk_bf16_f32 v52, v124, v125
	v_cvt_pk_bf16_f32 v53, v126, v127
	v_cvt_pk_bf16_f32 v54, v128, v129
	v_cvt_pk_bf16_f32 v55, v130, v131
	v_add_f32_e32 v116, v116, v117
	v_add_f32_e32 v118, v118, v119
	v_add_f32_e32 v120, v120, v121
	v_add_f32_e32 v122, v122, v123
	v_add_f32_e32 v124, v124, v125
	v_add_f32_e32 v126, v126, v127
	v_add_f32_e32 v128, v128, v129
	v_add_f32_e32 v130, v130, v131
	v_add_f32_e32 v116, v116, v118
	v_add_f32_e32 v120, v120, v122
	v_add_f32_e32 v124, v124, v126
	v_add_f32_e32 v128, v128, v130
	v_add_f32_e32 v116, v116, v120
	v_add_f32_e32 v124, v124, v128
	v_add_f32_e32 v116, v116, v124
	v_add_f32_e32 v164, v164, v116
	s_waitcnt lgkmcnt(0)
	v_mfma_f32_16x16x32_bf16 v[96:99], v[220:223], v[132:135], v[96:99]
	v_mfma_f32_16x16x32_bf16 v[84:87], v[220:223], v[140:143], v[84:87]
	v_mfma_f32_16x16x32_bf16 v[96:99], v[224:227], v[136:139], v[96:99]
	v_mfma_f32_16x16x32_bf16 v[84:87], v[224:227], v[52:55], v[84:87]
	v_mfma_f32_16x16x32_bf16 v[88:91], v[228:231], v[132:135], v[88:91]
	v_mfma_f32_16x16x32_bf16 v[76:79], v[228:231], v[140:143], v[76:79]
	v_mfma_f32_16x16x32_bf16 v[88:91], v[232:235], v[136:139], v[88:91]
	v_mfma_f32_16x16x32_bf16 v[76:79], v[232:235], v[52:55], v[76:79]
	v_mfma_f32_16x16x32_bf16 v[92:95], v[236:239], v[132:135], v[92:95]
	v_mfma_f32_16x16x32_bf16 v[80:83], v[236:239], v[140:143], v[80:83]
	v_mfma_f32_16x16x32_bf16 v[92:95], v[240:243], v[136:139], v[92:95]
	v_mfma_f32_16x16x32_bf16 v[80:83], v[240:243], v[52:55], v[80:83]
	v_mfma_f32_16x16x32_bf16 v[48:51], v[244:247], v[132:135], v[48:51]
	v_mfma_f32_16x16x32_bf16 v[56:59], v[244:247], v[140:143], v[56:59]
	v_mfma_f32_16x16x32_bf16 v[48:51], v[204:207], v[136:139], v[48:51]
	v_mfma_f32_16x16x32_bf16 v[56:59], v[204:207], v[52:55], v[56:59]
	s_branch .Lmla_bar0
.Lmla_mask0:
	s_lshl_b32 s65, s65, 6
	v_subrev_u32_e32 v248, s65, v151
	v_cmp_le_i32_e64 s[90:91], 0, v248
	v_cmp_le_i32_e64 s[92:93], 1, v248
	v_cmp_le_i32_e64 s[94:95], 2, v248
	v_cndmask_b32_e64 v24, v183, v24, s[90:91]
	v_cmp_le_i32_e64 s[90:91], 3, v248
	v_cndmask_b32_e64 v25, v183, v25, s[92:93]
	v_cmp_le_i32_e64 s[92:93], 16, v248
	v_cndmask_b32_e64 v26, v183, v26, s[94:95]
	v_cmp_le_i32_e64 s[94:95], 17, v248
	v_cndmask_b32_e64 v27, v183, v27, s[90:91]
	v_cmp_le_i32_e64 s[90:91], 18, v248
	v_cndmask_b32_e64 v28, v183, v28, s[92:93]
	v_cmp_le_i32_e64 s[92:93], 19, v248
	v_cndmask_b32_e64 v29, v183, v29, s[94:95]
	v_cmp_le_i32_e64 s[94:95], 32, v248
	v_cndmask_b32_e64 v30, v183, v30, s[90:91]
	v_cmp_le_i32_e64 s[90:91], 33, v248
	v_cndmask_b32_e64 v31, v183, v31, s[92:93]
	v_cmp_le_i32_e64 s[92:93], 34, v248
	v_cndmask_b32_e64 v32, v183, v32, s[94:95]
	v_cmp_le_i32_e64 s[94:95], 35, v248
	v_cndmask_b32_e64 v33, v183, v33, s[90:91]
	v_cmp_le_i32_e64 s[90:91], 48, v248
	v_cndmask_b32_e64 v34, v183, v34, s[92:93]
	v_cmp_le_i32_e64 s[92:93], 49, v248
	v_cndmask_b32_e64 v35, v183, v35, s[94:95]
	v_cmp_le_i32_e64 s[94:95], 50, v248
	v_cndmask_b32_e64 v36, v183, v36, s[90:91]
	v_cmp_le_i32_e64 s[90:91], 51, v248
	s_nop 1
	v_cndmask_b32_e64 v37, v183, v37, s[92:93]
	v_cndmask_b32_e64 v38, v183, v38, s[94:95]
	v_cndmask_b32_e64 v39, v183, v39, s[90:91]
	v_subrev_u32_e32 v249, s65, v153
	v_cmp_le_i32_e64 s[90:91], 0, v249
	v_cmp_le_i32_e64 s[92:93], 1, v249
	v_cmp_le_i32_e64 s[94:95], 2, v249
	v_cndmask_b32_e64 v40, v183, v40, s[90:91]
	v_cmp_le_i32_e64 s[90:91], 3, v249
	v_cndmask_b32_e64 v41, v183, v41, s[92:93]
	v_cmp_le_i32_e64 s[92:93], 16, v249
	v_cndmask_b32_e64 v42, v183, v42, s[94:95]
	v_cmp_le_i32_e64 s[94:95], 17, v249
	v_cndmask_b32_e64 v43, v183, v43, s[90:91]
	v_cmp_le_i32_e64 s[90:91], 18, v249
	v_cndmask_b32_e64 v44, v183, v44, s[92:93]
	v_cmp_le_i32_e64 s[92:93], 19, v249
	v_cndmask_b32_e64 v45, v183, v45, s[94:95]
	v_cmp_le_i32_e64 s[94:95], 32, v249
	v_cndmask_b32_e64 v46, v183, v46, s[90:91]
	v_cmp_le_i32_e64 s[90:91], 33, v249
	v_cndmask_b32_e64 v47, v183, v47, s[92:93]
	v_cmp_le_i32_e64 s[92:93], 34, v249
	v_cndmask_b32_e64 v212, v183, v212, s[94:95]
	v_cmp_le_i32_e64 s[94:95], 35, v249
	v_cndmask_b32_e64 v213, v183, v213, s[90:91]
	v_cmp_le_i32_e64 s[90:91], 48, v249
	v_cndmask_b32_e64 v214, v183, v214, s[92:93]
	v_cmp_le_i32_e64 s[92:93], 49, v249
	v_cndmask_b32_e64 v215, v183, v215, s[94:95]
	v_cmp_le_i32_e64 s[94:95], 50, v249
	v_cndmask_b32_e64 v216, v183, v216, s[90:91]
	v_cmp_le_i32_e64 s[90:91], 51, v249
	s_nop 1
	v_cndmask_b32_e64 v217, v183, v217, s[92:93]
	v_cndmask_b32_e64 v218, v183, v218, s[94:95]
	v_cndmask_b32_e64 v219, v183, v219, s[90:91]
	s_branch .Lmla_slow0_0
; #define LAS __attribute__((address_space(3)))
; template <int I0, int NQ, int VO> __device__ __forceinline__ void tile_y(LAS unsigned char* lds, float (&l)[2], f32x4 (&o)[2][4], f32x4 (&s)[2][4], int fr, int fq) {
;     bf16x8 pb[NQ][2];
; #pragma unroll
;     for (int q = 0; q < NQ; ++q) {
;         f32x4 (&sq)[4] = s[I0 + q];
;         f32x2_t rs2 = {0.f, 0.f};
; #pragma unroll
;         for (int ss = 0; ss < 4; ++ss) {
; #pragma unroll
;             for (int i = 0; i < 4; ++i) sq[ss][i] = __builtin_amdgcn_exp2f(sq[ss][i]);
;             rs2 += (f32x2_t){sq[ss][0], sq[ss][1]}; rs2 += (f32x2_t){sq[ss][2], sq[ss][3]};
;         }
;         l[I0 + q] += rs2.x + rs2.y;
; #pragma unroll
;         for (int j = 0; j < 2; ++j) {
;             const v4u w = (v4u){cvtpk(sq[2 * j][0], sq[2 * j][1]), cvtpk(sq[2 * j][2], sq[2 * j][3]), cvtpk(sq[2 * j + 1][0], sq[2 * j + 1][1]), cvtpk(sq[2 * j + 1][2], sq[2 * j + 1][3])};
;             pb[q][j] = __builtin_bit_cast(bf16x8, w);
;         }
; template <bool FULL> __device__ __forceinline__ void x2_tile(int kbase, const int (&tpos)[2], float (&m)[2], float (&l)[2], f32x4 (&o)[2][4], f32x4 (&s)[2][4], int fq) {
;     ...
;         if (slow) {
;             float mx;
;             if (FULL) {
;                 mx = fmaxf(fmaxf(sq[0][0], sq[0][1]), fmaxf(sq[0][2], sq[0][3]));
; #pragma unroll
;                 for (int ss = 1; ss < 4; ++ss) mx = fmaxf(mx, fmaxf(fmaxf(sq[ss][0], sq[ss][1]), fmaxf(sq[ss][2], sq[ss][3])));
;             } else {
;                 mx = NEG;
; #pragma unroll
;                 for (int ss = 0; ss < 4; ++ss)
; #pragma unroll
;                     for (int i = 0; i < 4; ++i) { const bool ok = (kbase + 16 * ss + 4 * fq + i) <= tpos[q]; const float v = ok ? sq[ss][i] : NEG; sq[ss][i] = v; mx = fmaxf(mx, v); }
;             }
;             mx = rows_max(mx);
;             const bool need = (mo > -1e29f) ? (mx > RESCALE_THR) : (mx > -1e29f);
;             if (__any(need ? 1 : 0)) {
;                 const float delta = need ? mx : 0.f; const float mnew = need ? meff + delta : mo; const float alpha = need ? __builtin_amdgcn_exp2f(mo - mnew) : 1.0f;
;                 l[q] *= alpha; m[q] = mnew;
; #pragma unroll
;                 for (int dt = 0; dt < 4; ++dt) o[q][dt] = o[q][dt] * alpha;
; #pragma unroll
;                 for (int ss = 0; ss < 4; ++ss) sq[ss] = sq[ss] - delta;
;             }
.Lmla_slow0_0:
	s_nop 7
	s_nop 7
	v_max3_f32 v72, v24, v25, v26
	v_max3_f32 v72, v72, v27, v28
	v_max3_f32 v72, v72, v29, v30
	v_max3_f32 v72, v72, v31, v32
	v_max3_f32 v72, v72, v33, v34
	v_max3_f32 v72, v72, v35, v36
	v_max3_f32 v72, v72, v37, v38
	v_max_f32_e32 v72, v72, v39
	v_mov_b32_e32 v73, v72
	s_nop 1
	v_permlane16_swap_b32_e32 v72, v73
	v_max_f32_e32 v72, v72, v73
	v_mov_b32_e32 v73, v72
	s_nop 1
	v_permlane32_swap_b32_e32 v72, v73
	v_max_f32_e32 v74, v72, v73
	v_cmp_lt_f32_e64 s[70:71], s80, v74
	v_cmp_lt_f32_e64 s[72:73], s77, v74
	s_and_b64 s[70:71], s[70:71], s[66:67]
	s_andn2_b64 s[72:73], s[72:73], s[66:67]
	s_or_b64 s[70:71], s[70:71], s[72:73]
	s_cmp_lg_u64 s[70:71], 0
	s_cbranch_scc0 .Lmla_chk0_1
	v_add_f32_e32 v72, v197, v74
	v_cndmask_b32_e64 v75, 0, v74, s[70:71]
	v_cndmask_b32_e64 v208, v200, v72, s[70:71]
	v_sub_f32_e32 v72, v200, v208
	v_exp_f32_e32 v72, v72
	v_mov_b32_e32 v200, v208
	v_cndmask_b32_e64 v209, 1.0, v72, s[70:71]
	v_mul_f32_e32 v165, v165, v209
	v_mul_f32_e32 v96, v96, v209
	v_mul_f32_e32 v97, v97, v209
	v_mul_f32_e32 v98, v98, v209
	v_mul_f32_e32 v99, v99, v209
	v_mul_f32_e32 v88, v88, v209
	v_mul_f32_e32 v89, v89, v209
	v_mul_f32_e32 v90, v90, v209
	v_mul_f32_e32 v91, v91, v209
	v_mul_f32_e32 v92, v92, v209
	v_mul_f32_e32 v93, v93, v209
	v_mul_f32_e32 v94, v94, v209
	v_mul_f32_e32 v95, v95, v209
	v_mul_f32_e32 v48, v48, v209
	v_mul_f32_e32 v49, v49, v209
	v_mul_f32_e32 v50, v50, v209
	v_mul_f32_e32 v51, v51, v209
	v_sub_f32_e32 v24, v24, v75
	v_sub_f32_e32 v25, v25, v75
	v_sub_f32_e32 v26, v26, v75
	v_sub_f32_e32 v27, v27, v75
	v_sub_f32_e32 v28, v28, v75
	v_sub_f32_e32 v29, v29, v75
	v_sub_f32_e32 v30, v30, v75
	v_sub_f32_e32 v31, v31, v75
	v_sub_f32_e32 v32, v32, v75
	v_sub_f32_e32 v33, v33, v75
	v_sub_f32_e32 v34, v34, v75
	v_sub_f32_e32 v35, v35, v75
	v_sub_f32_e32 v36, v36, v75
	v_sub_f32_e32 v37, v37, v75
	v_sub_f32_e32 v38, v38, v75
	v_sub_f32_e32 v39, v39, v75
	s_branch .Lmla_chk0_1
.Lmla_slow0_1:
	s_nop 7
	s_nop 7
	v_max3_f32 v72, v40, v41, v42
	v_max3_f32 v72, v72, v43, v44
	v_max3_f32 v72, v72, v45, v46
	v_max3_f32 v72, v72, v47, v212
	v_max3_f32 v72, v72, v213, v214
	v_max3_f32 v72, v72, v215, v216
	v_max3_f32 v72, v72, v217, v218
	v_max_f32_e32 v72, v72, v219
	v_mov_b32_e32 v73, v72
	s_nop 1
	v_permlane16_swap_b32_e32 v72, v73
	v_max_f32_e32 v72, v72, v73
	v_mov_b32_e32 v73, v72
	s_nop 1
	v_permlane32_swap_b32_e32 v72, v73
	v_max_f32_e32 v74, v72, v73
	v_cmp_lt_f32_e64 s[70:71], s80, v74
	v_cmp_lt_f32_e64 s[72:73], s77, v74
	s_and_b64 s[70:71], s[70:71], s[68:69]
	s_andn2_b64 s[72:73], s[72:73], s[68:69]
	s_or_b64 s[70:71], s[70:71], s[72:73]
	s_cmp_lg_u64 s[70:71], 0
	s_cbranch_scc0 .Lmla_bar0
	v_add_f32_e32 v72, v198, v74
	v_cndmask_b32_e64 v75, 0, v74, s[70:71]
	v_cndmask_b32_e64 v208, v211, v72, s[70:71]
	v_sub_f32_e32 v72, v211, v208
	v_exp_f32_e32 v72, v72
	v_mov_b32_e32 v211, v208
	v_cndmask_b32_e64 v209, 1.0, v72, s[70:71]
	v_mul_f32_e32 v164, v164, v209
	v_mul_f32_e32 v84, v84, v209
	v_mul_f32_e32 v85, v85, v209
	v_mul_f32_e32 v86, v86, v209
	v_mul_f32_e32 v87, v87, v209
	v_mul_f32_e32 v76, v76, v209
	v_mul_f32_e32 v77, v77, v209
	v_mul_f32_e32 v78, v78, v209
	v_mul_f32_e32 v79, v79, v209
	v_mul_f32_e32 v80, v80, v209
	v_mul_f32_e32 v81, v81, v209
	v_mul_f32_e32 v82, v82, v209
	v_mul_f32_e32 v83, v83, v209
	v_mul_f32_e32 v56, v56, v209
	v_mul_f32_e32 v57, v57, v209
	v_mul_f32_e32 v58, v58, v209
	v_mul_f32_e32 v59, v59, v209
	v_sub_f32_e32 v40, v40, v75
	v_sub_f32_e32 v41, v41, v75
	v_sub_f32_e32 v42, v42, v75
	v_sub_f32_e32 v43, v43, v75
	v_sub_f32_e32 v44, v44, v75
	v_sub_f32_e32 v45, v45, v75
	v_sub_f32_e32 v46, v46, v75
	v_sub_f32_e32 v47, v47, v75
	v_sub_f32_e32 v212, v212, v75
	v_sub_f32_e32 v213, v213, v75
	v_sub_f32_e32 v214, v214, v75
	v_sub_f32_e32 v215, v215, v75
	v_sub_f32_e32 v216, v216, v75
	v_sub_f32_e32 v217, v217, v75
	v_sub_f32_e32 v218, v218, v75
	v_sub_f32_e32 v219, v219, v75
	s_branch .Lmla_bar0
.Lmla_last1:
	v_add_u32_e32 v74, s60, v251
	ds_read_b64_tr_b16 v[236:237], v74 offset:16448
	ds_read_b64_tr_b16 v[238:239], v74 offset:19008
	ds_read_b64_tr_b16 v[240:241], v74 offset:21568
	ds_read_b64_tr_b16 v[242:243], v74 offset:24128
	ds_read_b64_tr_b16 v[244:245], v74 offset:16480
	ds_read_b64_tr_b16 v[246:247], v74 offset:19040
	ds_read_b64_tr_b16 v[204:205], v74 offset:21600
	ds_read_b64_tr_b16 v[206:207], v74 offset:24160
	v_exp_f32_e32 v24, v24
	v_exp_f32_e32 v25, v25
	v_exp_f32_e32 v26, v26
	v_exp_f32_e32 v27, v27
	v_exp_f32_e32 v28, v28
	v_exp_f32_e32 v29, v29
	v_exp_f32_e32 v30, v30
	v_exp_f32_e32 v31, v31
	v_exp_f32_e32 v32, v32
	v_exp_f32_e32 v33, v33
	v_exp_f32_e32 v34, v34
	v_exp_f32_e32 v35, v35
	v_exp_f32_e32 v36, v36
	v_exp_f32_e32 v37, v37
	v_exp_f32_e32 v38, v38
	v_exp_f32_e32 v39, v39
	v_cvt_pk_bf16_f32 v132, v24, v25
	v_cvt_pk_bf16_f32 v133, v26, v27
	v_cvt_pk_bf16_f32 v134, v28, v29
	v_cvt_pk_bf16_f32 v135, v30, v31
	v_cvt_pk_bf16_f32 v136, v32, v33
	v_cvt_pk_bf16_f32 v137, v34, v35
	v_cvt_pk_bf16_f32 v138, v36, v37
	v_cvt_pk_bf16_f32 v139, v38, v39
	v_add_f32_e32 v24, v24, v25
	v_add_f32_e32 v26, v26, v27
	v_add_f32_e32 v28, v28, v29
	v_add_f32_e32 v30, v30, v31
	v_add_f32_e32 v32, v32, v33
	v_add_f32_e32 v34, v34, v35
	v_add_f32_e32 v36, v36, v37
	v_add_f32_e32 v38, v38, v39
	v_add_f32_e32 v24, v24, v26
	v_add_f32_e32 v28, v28, v30
	v_add_f32_e32 v32, v32, v34
	v_add_f32_e32 v36, v36, v38
	v_add_f32_e32 v24, v24, v28
	v_add_f32_e32 v32, v32, v36
	v_add_f32_e32 v24, v24, v32
	v_add_f32_e32 v165, v165, v24
	v_exp_f32_e32 v40, v40
	v_exp_f32_e32 v41, v41
	v_exp_f32_e32 v42, v42
	v_exp_f32_e32 v43, v43
	v_exp_f32_e32 v44, v44
	v_exp_f32_e32 v45, v45
	v_exp_f32_e32 v46, v46
	v_exp_f32_e32 v47, v47
	v_exp_f32_e32 v212, v212
	v_exp_f32_e32 v213, v213
	v_exp_f32_e32 v214, v214
	v_exp_f32_e32 v215, v215
	v_exp_f32_e32 v216, v216
	v_exp_f32_e32 v217, v217
	v_exp_f32_e32 v218, v218
	v_exp_f32_e32 v219, v219
	v_cvt_pk_bf16_f32 v140, v40, v41
	v_cvt_pk_bf16_f32 v141, v42, v43
	v_cvt_pk_bf16_f32 v142, v44, v45
	v_cvt_pk_bf16_f32 v143, v46, v47
	v_cvt_pk_bf16_f32 v52, v212, v213
	v_cvt_pk_bf16_f32 v53, v214, v215
	v_cvt_pk_bf16_f32 v54, v216, v217
	v_cvt_pk_bf16_f32 v55, v218, v219
	v_add_f32_e32 v40, v40, v41
	v_add_f32_e32 v42, v42, v43
	v_add_f32_e32 v44, v44, v45
	v_add_f32_e32 v46, v46, v47
	v_add_f32_e32 v212, v212, v213
	v_add_f32_e32 v214, v214, v215
	v_add_f32_e32 v216, v216, v217
	v_add_f32_e32 v218, v218, v219
	v_add_f32_e32 v40, v40, v42
	v_add_f32_e32 v44, v44, v46
	v_add_f32_e32 v212, v212, v214
	v_add_f32_e32 v216, v216, v218
	v_add_f32_e32 v40, v40, v44
	v_add_f32_e32 v212, v212, v216
	v_add_f32_e32 v40, v40, v212
	v_add_f32_e32 v164, v164, v40
	s_waitcnt lgkmcnt(0)
; #define LAS __attribute__((address_space(3)))
; template <int I0, int NQ, int VO> __device__ __forceinline__ void tile_y(LAS unsigned char* lds, float (&l)[2], f32x4 (&o)[2][4], f32x4 (&s)[2][4], int fr, int fq) {
;     ...
; #pragma unroll
;     for (int dt = 0; dt < 4; ++dt)
; #pragma unroll
;         for (int j = 0; j < 2; ++j) {
;             LAS unsigned char* vp = lds + VO + ((32 * j + 4 * fq + (fr >> 2)) * VSTR + 16 * dt + 4 * (fr & 3)) * 2;
;             const s16x4 lo = __builtin_bit_cast(s16x4, __builtin_amdgcn_ds_read_tr16_b64_v4i16((LAS v4i16_t*)vp));
;             const s16x4 hi = __builtin_bit_cast(s16x4, __builtin_amdgcn_ds_read_tr16_b64_v4i16((LAS v4i16_t*)(vp + 16 * VSTR * 2)));
;             const bf16x8 vf = (bf16x8){lo[0], lo[1], lo[2], lo[3], hi[0], hi[1], hi[2], hi[3]};
; #pragma unroll
;             for (int q = 0; q < NQ; ++q) o[I0 + q][dt] = __builtin_amdgcn_mfma_f32_16x16x32_bf16(vf, pb[q][j], o[I0 + q][dt], 0, 0, 0);
;         }
; template <bool FULL> __device__ __forceinline__ void x2_tile(int kbase, const int (&tpos)[2], float (&m)[2], float (&l)[2], f32x4 (&o)[2][4], f32x4 (&s)[2][4], int fq) {
;     ...
;                 mx = NEG;
; #pragma unroll
;                 for (int ss = 0; ss < 4; ++ss)
; #pragma unroll
;                     for (int i = 0; i < 4; ++i) { const bool ok = (kbase + 16 * ss + 4 * fq + i) <= tpos[q]; const float v = ok ? sq[ss][i] : NEG; sq[ss][i] = v; mx = fmaxf(mx, v); }
	v_mfma_f32_16x16x32_bf16 v[96:99], v[220:223], v[132:135], v[96:99]
	v_mfma_f32_16x16x32_bf16 v[84:87], v[220:223], v[140:143], v[84:87]
	v_mfma_f32_16x16x32_bf16 v[96:99], v[224:227], v[136:139], v[96:99]
	v_mfma_f32_16x16x32_bf16 v[84:87], v[224:227], v[52:55], v[84:87]
	v_mfma_f32_16x16x32_bf16 v[88:91], v[228:231], v[132:135], v[88:91]
	v_mfma_f32_16x16x32_bf16 v[76:79], v[228:231], v[140:143], v[76:79]
	v_mfma_f32_16x16x32_bf16 v[88:91], v[232:235], v[136:139], v[88:91]
	v_mfma_f32_16x16x32_bf16 v[76:79], v[232:235], v[52:55], v[76:79]
	v_mfma_f32_16x16x32_bf16 v[92:95], v[236:239], v[132:135], v[92:95]
	v_mfma_f32_16x16x32_bf16 v[80:83], v[236:239], v[140:143], v[80:83]
	v_mfma_f32_16x16x32_bf16 v[92:95], v[240:243], v[136:139], v[92:95]
	v_mfma_f32_16x16x32_bf16 v[80:83], v[240:243], v[52:55], v[80:83]
	v_mfma_f32_16x16x32_bf16 v[48:51], v[244:247], v[132:135], v[48:51]
	v_mfma_f32_16x16x32_bf16 v[56:59], v[244:247], v[140:143], v[56:59]
	v_mfma_f32_16x16x32_bf16 v[48:51], v[204:207], v[136:139], v[48:51]
	v_mfma_f32_16x16x32_bf16 v[56:59], v[204:207], v[52:55], v[56:59]
	s_branch .Lmla_bar1
.Lmla_mask1:
	s_lshl_b32 s65, s65, 6
	v_subrev_u32_e32 v248, s65, v151
	v_cmp_le_i32_e64 s[90:91], 0, v248
	v_cmp_le_i32_e64 s[92:93], 1, v248
	v_cmp_le_i32_e64 s[94:95], 2, v248
	v_cndmask_b32_e64 v100, v183, v100, s[90:91]
	v_cmp_le_i32_e64 s[90:91], 3, v248
	v_cndmask_b32_e64 v101, v183, v101, s[92:93]
	v_cmp_le_i32_e64 s[92:93], 16, v248
	v_cndmask_b32_e64 v102, v183, v102, s[94:95]
	v_cmp_le_i32_e64 s[94:95], 17, v248
	v_cndmask_b32_e64 v103, v183, v103, s[90:91]
	v_cmp_le_i32_e64 s[90:91], 18, v248
	v_cndmask_b32_e64 v104, v183, v104, s[92:93]
	v_cmp_le_i32_e64 s[92:93], 19, v248
	v_cndmask_b32_e64 v105, v183, v105, s[94:95]
	v_cmp_le_i32_e64 s[94:95], 32, v248
	v_cndmask_b32_e64 v106, v183, v106, s[90:91]
	v_cmp_le_i32_e64 s[90:91], 33, v248
	v_cndmask_b32_e64 v107, v183, v107, s[92:93]
	v_cmp_le_i32_e64 s[92:93], 34, v248
	v_cndmask_b32_e64 v108, v183, v108, s[94:95]
	v_cmp_le_i32_e64 s[94:95], 35, v248
	v_cndmask_b32_e64 v109, v183, v109, s[90:91]
	v_cmp_le_i32_e64 s[90:91], 48, v248
	v_cndmask_b32_e64 v110, v183, v110, s[92:93]
	v_cmp_le_i32_e64 s[92:93], 49, v248
	v_cndmask_b32_e64 v111, v183, v111, s[94:95]
	v_cmp_le_i32_e64 s[94:95], 50, v248
	v_cndmask_b32_e64 v112, v183, v112, s[90:91]
	v_cmp_le_i32_e64 s[90:91], 51, v248
	s_nop 1
	v_cndmask_b32_e64 v113, v183, v113, s[92:93]
	v_cndmask_b32_e64 v114, v183, v114, s[94:95]
	v_cndmask_b32_e64 v115, v183, v115, s[90:91]
	v_subrev_u32_e32 v249, s65, v153
	v_cmp_le_i32_e64 s[90:91], 0, v249
	v_cmp_le_i32_e64 s[92:93], 1, v249
	v_cmp_le_i32_e64 s[94:95], 2, v249
	v_cndmask_b32_e64 v116, v183, v116, s[90:91]
	v_cmp_le_i32_e64 s[90:91], 3, v249
	v_cndmask_b32_e64 v117, v183, v117, s[92:93]
	v_cmp_le_i32_e64 s[92:93], 16, v249
	v_cndmask_b32_e64 v118, v183, v118, s[94:95]
	v_cmp_le_i32_e64 s[94:95], 17, v249
	v_cndmask_b32_e64 v119, v183, v119, s[90:91]
	v_cmp_le_i32_e64 s[90:91], 18, v249
	v_cndmask_b32_e64 v120, v183, v120, s[92:93]
	v_cmp_le_i32_e64 s[92:93], 19, v249
	v_cndmask_b32_e64 v121, v183, v121, s[94:95]
	v_cmp_le_i32_e64 s[94:95], 32, v249
	v_cndmask_b32_e64 v122, v183, v122, s[90:91]
	v_cmp_le_i32_e64 s[90:91], 33, v249
	v_cndmask_b32_e64 v123, v183, v123, s[92:93]
	v_cmp_le_i32_e64 s[92:93], 34, v249
	v_cndmask_b32_e64 v124, v183, v124, s[94:95]
	v_cmp_le_i32_e64 s[94:95], 35, v249
	v_cndmask_b32_e64 v125, v183, v125, s[90:91]
	v_cmp_le_i32_e64 s[90:91], 48, v249
	v_cndmask_b32_e64 v126, v183, v126, s[92:93]
	v_cmp_le_i32_e64 s[92:93], 49, v249
	v_cndmask_b32_e64 v127, v183, v127, s[94:95]
	v_cmp_le_i32_e64 s[94:95], 50, v249
	v_cndmask_b32_e64 v128, v183, v128, s[90:91]
	v_cmp_le_i32_e64 s[90:91], 51, v249
	s_nop 1
	v_cndmask_b32_e64 v129, v183, v129, s[92:93]
	v_cndmask_b32_e64 v130, v183, v130, s[94:95]
	v_cndmask_b32_e64 v131, v183, v131, s[90:91]
	s_branch .Lmla_slow1_0
; template <bool FULL> __device__ __forceinline__ void x2_tile(int kbase, const int (&tpos)[2], float (&m)[2], float (&l)[2], f32x4 (&o)[2][4], f32x4 (&s)[2][4], int fq) {
;     ...
;         if (slow) {
;             float mx;
;             if (FULL) {
;                 mx = fmaxf(fmaxf(sq[0][0], sq[0][1]), fmaxf(sq[0][2], sq[0][3]));
; #pragma unroll
;                 for (int ss = 1; ss < 4; ++ss) mx = fmaxf(mx, fmaxf(fmaxf(sq[ss][0], sq[ss][1]), fmaxf(sq[ss][2], sq[ss][3])));
;             } else {
;                 mx = NEG;
; #pragma unroll
;                 for (int ss = 0; ss < 4; ++ss)
; #pragma unroll
;                     for (int i = 0; i < 4; ++i) { const bool ok = (kbase + 16 * ss + 4 * fq + i) <= tpos[q]; const float v = ok ? sq[ss][i] : NEG; sq[ss][i] = v; mx = fmaxf(mx, v); }
;             }
;             mx = rows_max(mx);
;             const bool need = (mo > -1e29f) ? (mx > RESCALE_THR) : (mx > -1e29f);
;             if (__any(need ? 1 : 0)) {
;                 const float delta = need ? mx : 0.f; const float mnew = need ? meff + delta : mo; const float alpha = need ? __builtin_amdgcn_exp2f(mo - mnew) : 1.0f;
;                 l[q] *= alpha; m[q] = mnew;
; #pragma unroll
;                 for (int dt = 0; dt < 4; ++dt) o[q][dt] = o[q][dt] * alpha;
; #pragma unroll
;                 for (int ss = 0; ss < 4; ++ss) sq[ss] = sq[ss] - delta;
;             }
.Lmla_slow1_0:
	s_nop 7
	s_nop 7
	v_max3_f32 v72, v100, v101, v102
	v_max3_f32 v72, v72, v103, v104
	v_max3_f32 v72, v72, v105, v106
	v_max3_f32 v72, v72, v107, v108
	v_max3_f32 v72, v72, v109, v110
	v_max3_f32 v72, v72, v111, v112
	v_max3_f32 v72, v72, v113, v114
	v_max_f32_e32 v72, v72, v115
	v_mov_b32_e32 v73, v72
	s_nop 1
	v_permlane16_swap_b32_e32 v72, v73
	v_max_f32_e32 v72, v72, v73
	v_mov_b32_e32 v73, v72
	s_nop 1
	v_permlane32_swap_b32_e32 v72, v73
	v_max_f32_e32 v74, v72, v73
	v_cmp_lt_f32_e64 s[70:71], s80, v74
	v_cmp_lt_f32_e64 s[72:73], s77, v74
	s_and_b64 s[70:71], s[70:71], s[66:67]
	s_andn2_b64 s[72:73], s[72:73], s[66:67]
	s_or_b64 s[70:71], s[70:71], s[72:73]
	s_cmp_lg_u64 s[70:71], 0
	s_cbranch_scc0 .Lmla_chk1_1
	v_add_f32_e32 v72, v197, v74
	v_cndmask_b32_e64 v75, 0, v74, s[70:71]
	v_cndmask_b32_e64 v208, v200, v72, s[70:71]
	v_sub_f32_e32 v72, v200, v208
	v_exp_f32_e32 v72, v72
	v_mov_b32_e32 v200, v208
	v_cndmask_b32_e64 v209, 1.0, v72, s[70:71]
	v_mul_f32_e32 v165, v165, v209
	v_mul_f32_e32 v96, v96, v209
	v_mul_f32_e32 v97, v97, v209
	v_mul_f32_e32 v98, v98, v209
	v_mul_f32_e32 v99, v99, v209
	v_mul_f32_e32 v88, v88, v209
	v_mul_f32_e32 v89, v89, v209
	v_mul_f32_e32 v90, v90, v209
	v_mul_f32_e32 v91, v91, v209
	v_mul_f32_e32 v92, v92, v209
	v_mul_f32_e32 v93, v93, v209
	v_mul_f32_e32 v94, v94, v209
	v_mul_f32_e32 v95, v95, v209
	v_mul_f32_e32 v48, v48, v209
	v_mul_f32_e32 v49, v49, v209
	v_mul_f32_e32 v50, v50, v209
	v_mul_f32_e32 v51, v51, v209
	v_sub_f32_e32 v100, v100, v75
	v_sub_f32_e32 v101, v101, v75
	v_sub_f32_e32 v102, v102, v75
	v_sub_f32_e32 v103, v103, v75
	v_sub_f32_e32 v104, v104, v75
	v_sub_f32_e32 v105, v105, v75
	v_sub_f32_e32 v106, v106, v75
	v_sub_f32_e32 v107, v107, v75
	v_sub_f32_e32 v108, v108, v75
	v_sub_f32_e32 v109, v109, v75
	v_sub_f32_e32 v110, v110, v75
	v_sub_f32_e32 v111, v111, v75
	v_sub_f32_e32 v112, v112, v75
	v_sub_f32_e32 v113, v113, v75
	v_sub_f32_e32 v114, v114, v75
	v_sub_f32_e32 v115, v115, v75
	s_branch .Lmla_chk1_1
.Lmla_slow1_1:
	s_nop 7
	s_nop 7
	v_max3_f32 v72, v116, v117, v118
	v_max3_f32 v72, v72, v119, v120
	v_max3_f32 v72, v72, v121, v122
	v_max3_f32 v72, v72, v123, v124
	v_max3_f32 v72, v72, v125, v126
	v_max3_f32 v72, v72, v127, v128
	v_max3_f32 v72, v72, v129, v130
	v_max_f32_e32 v72, v72, v131
	v_mov_b32_e32 v73, v72
	s_nop 1
	v_permlane16_swap_b32_e32 v72, v73
	v_max_f32_e32 v72, v72, v73
	v_mov_b32_e32 v73, v72
	s_nop 1
	v_permlane32_swap_b32_e32 v72, v73
	v_max_f32_e32 v74, v72, v73
	v_cmp_lt_f32_e64 s[70:71], s80, v74
	v_cmp_lt_f32_e64 s[72:73], s77, v74
	s_and_b64 s[70:71], s[70:71], s[68:69]
	s_andn2_b64 s[72:73], s[72:73], s[68:69]
	s_or_b64 s[70:71], s[70:71], s[72:73]
	s_cmp_lg_u64 s[70:71], 0
	s_cbranch_scc0 .Lmla_bar1
	v_add_f32_e32 v72, v198, v74
	v_cndmask_b32_e64 v75, 0, v74, s[70:71]
	v_cndmask_b32_e64 v208, v211, v72, s[70:71]
	v_sub_f32_e32 v72, v211, v208
	v_exp_f32_e32 v72, v72
	v_mov_b32_e32 v211, v208
	v_cndmask_b32_e64 v209, 1.0, v72, s[70:71]
	v_mul_f32_e32 v164, v164, v209
	v_mul_f32_e32 v84, v84, v209
	v_mul_f32_e32 v85, v85, v209
	v_mul_f32_e32 v86, v86, v209
	v_mul_f32_e32 v87, v87, v209
	v_mul_f32_e32 v76, v76, v209
	v_mul_f32_e32 v77, v77, v209
	v_mul_f32_e32 v78, v78, v209
	v_mul_f32_e32 v79, v79, v209
	v_mul_f32_e32 v80, v80, v209
	v_mul_f32_e32 v81, v81, v209
	v_mul_f32_e32 v82, v82, v209
	v_mul_f32_e32 v83, v83, v209
	v_mul_f32_e32 v56, v56, v209
	v_mul_f32_e32 v57, v57, v209
	v_mul_f32_e32 v58, v58, v209
	v_mul_f32_e32 v59, v59, v209
	v_sub_f32_e32 v116, v116, v75
	v_sub_f32_e32 v117, v117, v75
	v_sub_f32_e32 v118, v118, v75
	v_sub_f32_e32 v119, v119, v75
	v_sub_f32_e32 v120, v120, v75
	v_sub_f32_e32 v121, v121, v75
	v_sub_f32_e32 v122, v122, v75
	v_sub_f32_e32 v123, v123, v75
	v_sub_f32_e32 v124, v124, v75
	v_sub_f32_e32 v125, v125, v75
	v_sub_f32_e32 v126, v126, v75
	v_sub_f32_e32 v127, v127, v75
	v_sub_f32_e32 v128, v128, v75
	v_sub_f32_e32 v129, v129, v75
	v_sub_f32_e32 v130, v130, v75
	v_sub_f32_e32 v131, v131, v75
	s_branch .Lmla_bar1
